# attention fast loop: dropped provably-zero 64-bit adds from DMA address calc (v2 structure)
# speedup vs baseline: 1.0017x; 1.0017x over previous
; __device__ __forceinline__ void finishSM_fix(f32x16& p0, f32x16& p1, float& l_lane, bf16x8& pa0, bf16x8& pa1, bf16x8& pa2, bf16x8& pa3) {
; #pragma unroll
;   for (int r = 0; r < 16; ++r) p1[r] = __builtin_amdgcn_exp2f(p1[r]);
;   float ps = 0;
; #pragma unroll
;   for (int r = 0; r < 16; ++r) ps += p0[r];
; #pragma unroll
;   for (int r = 0; r < 16; ++r) ps += p1[r];
;   l_lane += ps;
;     ...
;   PK4(p0, 0, pa0); PK4(p0, 8, pa1); PK4(p1, 0, pa2); PK4(p1, 8, pa3);
; __device__ __forceinline__ void qkt12(f32x16& p0, f32x16& p1, const char* Ks, const bf16x8 (&qr)[12], const int (&kb)[4]) {
;   p0 = f32x16{}; p1 = f32x16{};
;     ...
;   bf16x8 c0 = KLD(0, 0), c1 = KLD(0, 1);
; #pragma unroll
;   for (int d0 = 0; d0 < 12; ++d0) {
;     bf16x8 n0 = c0, n1 = c1;
;     if (d0 < 11) { n0 = KLD(d0 + 1, 0); n1 = KLD(d0 + 1, 1); }
;     __builtin_amdgcn_sched_group_barrier(0x100, 2, 0);
;     p0 = __builtin_amdgcn_mfma_f32_32x32x16_bf16(c0, qr[d0], p0, 0, 0, 0);
;     p1 = __builtin_amdgcn_mfma_f32_32x32x16_bf16(c1, qr[d0], p1, 0, 0, 0);
;     __builtin_amdgcn_sched_group_barrier(0x008, 2, 0);
;     c0 = n0; c1 = n1; }
;     ...
; }
.Lfa_loop:
	s_add_i32 s22, s26, 1
	s_cmp_lg_u32 s26, 2
	s_cselect_b32 s24, s22, 0
	s_add_i32 s22, s24, 1
	s_cmp_lg_u32 s24, 2
	s_cselect_b32 s25, s22, 0
	s_waitcnt vmcnt(5)
	s_barrier
	s_mul_i32 s6, s24, 0x6000
	s_mul_i32 s10, s26, 0x6000
	s_lshl_b32 s11, s25, 14
	s_add_i32 s10, s43, s10
	s_add_i32 s11, s52, s11
	v_add_u32_e32 v187, s6, v183
	v_add_u32_e32 v188, s6, v184
	v_add_u32_e32 v189, s6, v185
	v_add_u32_e32 v190, s6, v186
	v_lshl_add_u32 v191, s26, 14, v182
	ds_read_b128 v[172:175], v187
	ds_read_b128 v[176:179], v187 offset:12288
	ds_read_b128 v[200:203], v188
	ds_read_b128 v[204:207], v188 offset:12288
	v_add_f32_e32 v196, v82, v83
	v_cvt_pk_bf16_f32 v82, v82, v83
	v_add_f32_e32 v197, v84, v85
	v_exp_f32_e32 v66, v66
	v_exp_f32_e32 v67, v67
	v_cvt_pk_bf16_f32 v83, v84, v85
	v_add_f32_e32 v196, v86, v196
	v_add_f32_e32 v197, v87, v197
	s_waitcnt lgkmcnt(3)
	v_mfma_f32_32x32x16_bf16 v[98:113], v[172:175], v[116:119], 0
	v_exp_f32_e32 v68, v68
	v_exp_f32_e32 v69, v69
	s_waitcnt lgkmcnt(2)
	v_mfma_f32_32x32x16_bf16 v[212:227], v[176:179], v[116:119], 0
	ds_read_b128 v[172:175], v189
	ds_read_b128 v[176:179], v189 offset:12288
	v_cvt_pk_bf16_f32 v84, v86, v87
	v_add_f32_e32 v196, v88, v196
	v_add_f32_e32 v197, v89, v197
	v_exp_f32_e32 v70, v70
	s_waitcnt lgkmcnt(3)
	v_mfma_f32_32x32x16_bf16 v[98:113], v[200:203], v[120:123], v[98:113]
	s_mov_b32 m0, s10
	v_lshl_add_u64 v[192:193], v[166:167], 0, s[92:93]
	global_load_lds_dwordx4 v[192:193], off
	v_exp_f32_e32 v71, v71
	s_waitcnt lgkmcnt(2)
	v_mfma_f32_32x32x16_bf16 v[212:227], v[204:207], v[120:123], v[212:227]
	ds_read_b128 v[200:203], v190
	ds_read_b128 v[204:207], v190 offset:12288
	v_cvt_pk_bf16_f32 v85, v88, v89
	v_add_f32_e32 v196, v90, v196
	v_add_f32_e32 v197, v91, v197
	v_exp_f32_e32 v72, v72
	s_waitcnt lgkmcnt(3)
	v_mfma_f32_32x32x16_bf16 v[98:113], v[172:175], v[124:127], v[98:113]
	v_exp_f32_e32 v73, v73
	s_waitcnt lgkmcnt(2)
	v_mfma_f32_32x32x16_bf16 v[212:227], v[176:179], v[124:127], v[212:227]
	ds_read_b128 v[172:175], v187 offset:128
	ds_read_b128 v[176:179], v187 offset:12416
	v_cvt_pk_bf16_f32 v86, v90, v91
	v_add_f32_e32 v196, v92, v196
	v_add_f32_e32 v197, v93, v197
	v_exp_f32_e32 v74, v74
	s_waitcnt lgkmcnt(3)
	v_mfma_f32_32x32x16_bf16 v[98:113], v[200:203], v[128:131], v[98:113]
	s_add_i32 m0, s10, 0x400
	v_lshl_add_u64 v[192:193], v[168:169], 0, s[92:93]
	global_load_lds_dwordx4 v[192:193], off
	v_exp_f32_e32 v75, v75
	v_cvt_pk_bf16_f32 v87, v92, v93
	s_waitcnt lgkmcnt(2)
	v_mfma_f32_32x32x16_bf16 v[212:227], v[204:207], v[128:131], v[212:227]
	ds_read_b128 v[200:203], v188 offset:128
	ds_read_b128 v[204:207], v188 offset:12416
	v_add_f32_e32 v196, v94, v196
	v_add_f32_e32 v197, v95, v197
	v_exp_f32_e32 v76, v76
	s_waitcnt lgkmcnt(3)
	v_mfma_f32_32x32x16_bf16 v[98:113], v[172:175], v[132:135], v[98:113]
	v_exp_f32_e32 v77, v77
	v_cvt_pk_bf16_f32 v88, v94, v95
	s_waitcnt lgkmcnt(2)
	v_mfma_f32_32x32x16_bf16 v[212:227], v[176:179], v[132:135], v[212:227]
	ds_read_b128 v[172:175], v189 offset:128
	ds_read_b128 v[176:179], v189 offset:12416
	v_add_f32_e32 v196, v96, v196
	v_add_f32_e32 v197, v97, v197
	v_exp_f32_e32 v78, v78
	s_waitcnt lgkmcnt(3)
	v_mfma_f32_32x32x16_bf16 v[98:113], v[200:203], v[136:139], v[98:113]
	s_add_i32 m0, s10, 0x800
	v_lshl_add_u64 v[192:193], v[170:171], 0, s[92:93]
	global_load_lds_dwordx4 v[192:193], off
	v_exp_f32_e32 v79, v79
	v_cvt_pk_bf16_f32 v89, v96, v97
	s_waitcnt lgkmcnt(2)
	v_mfma_f32_32x32x16_bf16 v[212:227], v[204:207], v[136:139], v[212:227]
	ds_read_b128 v[200:203], v190 offset:128
	ds_read_b128 v[204:207], v190 offset:12416
	v_exp_f32_e32 v80, v80
	v_exp_f32_e32 v81, v81
	s_waitcnt lgkmcnt(3)
	v_mfma_f32_32x32x16_bf16 v[98:113], v[172:175], v[140:143], v[98:113]
	v_add_f32_e32 v196, v66, v196
	v_add_f32_e32 v197, v67, v197
	v_cvt_pk_bf16_f32 v66, v66, v67
	s_waitcnt lgkmcnt(2)
	v_mfma_f32_32x32x16_bf16 v[212:227], v[176:179], v[140:143], v[212:227]
	ds_read_b128 v[172:175], v187 offset:256
	ds_read_b128 v[176:179], v187 offset:12544
	v_permlane32_swap_b32_e32 v82, v84
	v_permlane32_swap_b32_e32 v83, v85
	v_permlane32_swap_b32_e32 v86, v88
	v_permlane32_swap_b32_e32 v87, v89
	s_waitcnt lgkmcnt(3)
	v_mfma_f32_32x32x16_bf16 v[98:113], v[200:203], v[144:147], v[98:113]
	s_mov_b64 s[22:23], 0x61e0c100
	s_mov_b32 m0, s11
	v_lshl_add_u64 v[192:193], v[164:165], 0, s[22:23]
	global_load_lds_dwordx4 v[192:193], off
	v_add_f32_e32 v196, v68, v196
	v_add_f32_e32 v197, v69, v197
	v_cvt_pk_bf16_f32 v67, v68, v69
	s_waitcnt lgkmcnt(2)
	v_mfma_f32_32x32x16_bf16 v[212:227], v[204:207], v[144:147], v[212:227]
	ds_read_b128 v[200:203], v188 offset:256
	ds_read_b128 v[204:207], v188 offset:12544
	v_add_f32_e32 v196, v70, v196
	v_add_f32_e32 v197, v71, v197
	v_cvt_pk_bf16_f32 v68, v70, v71
	v_add_f32_e32 v196, v72, v196
	s_waitcnt lgkmcnt(3)
	v_mfma_f32_32x32x16_bf16 v[98:113], v[172:175], v[152:155], v[98:113]
	ds_read_b64_tr_b16 v[228:229], v191 offset:0
	ds_read_b64_tr_b16 v[230:231], v191 offset:2048
	v_add_f32_e32 v197, v73, v197
	v_cvt_pk_bf16_f32 v69, v72, v73
	v_add_f32_e32 v196, v74, v196
	v_add_f32_e32 v197, v75, v197
	s_waitcnt lgkmcnt(4)
	v_mfma_f32_32x32x16_bf16 v[212:227], v[176:179], v[152:155], v[212:227]
	ds_read_b128 v[172:175], v189 offset:256
	ds_read_b128 v[176:179], v189 offset:12544
	ds_read_b64_tr_b16 v[232:233], v191 offset:4096
	ds_read_b64_tr_b16 v[234:235], v191 offset:6144
	v_cvt_pk_bf16_f32 v70, v74, v75
	v_add_f32_e32 v196, v76, v196
	v_add_f32_e32 v197, v77, v197
	s_waitcnt lgkmcnt(7)
; #define SBAR() __builtin_amdgcn_sched_barrier(0)
; __device__ __forceinline__ void partialSM_fix(f32x16& p0, f32x16& p1) {
; #pragma unroll
;   for (int r = 0; r < 16; ++r) p0[r] = __builtin_amdgcn_exp2f(p0[r]);
; }
; __device__ __forceinline__ void finishSM_fix(f32x16& p0, f32x16& p1, float& l_lane, bf16x8& pa0, bf16x8& pa1, bf16x8& pa2, bf16x8& pa3) {
; #pragma unroll
;   for (int r = 0; r < 16; ++r) p1[r] = __builtin_amdgcn_exp2f(p1[r]);
;   float ps = 0;
; #pragma unroll
;   for (int r = 0; r < 16; ++r) ps += p0[r];
; #pragma unroll
;   for (int r = 0; r < 16; ++r) ps += p1[r];
;   l_lane += ps;
;     ...
;   PK4(p0, 0, pa0); PK4(p0, 8, pa1); PK4(p1, 0, pa2); PK4(p1, 8, pa3);
; template <int OFF> __device__ __forceinline__ s16x4 tr_read(int vb) {
;   s16x4 r; asm volatile("ds_read_b64_tr_b16 %0, %1 offset:%2" : "=&v"(r) : "v"(vb), "i"(OFF) : "memory"); return r;
; }
; template <int D0> __device__ __forceinline__ void pv_one(f32x16& od, int vb, bf16x8 pa0, bf16x8 pa1, bf16x8 pa2, bf16x8 pa3) {
;   const s16x4 l0 = tr_read<v_rd_off(D0, 0, 0)>(vb), h0 = tr_read<v_rd_off(D0, 0, 1)>(vb), l1 = tr_read<v_rd_off(D0, 1, 0)>(vb), h1 = tr_read<v_rd_off(D0, 1, 1)>(vb);
;   const s16x4 l2 = tr_read<v_rd_off(D0, 2, 0)>(vb), h2 = tr_read<v_rd_off(D0, 2, 1)>(vb), l3 = tr_read<v_rd_off(D0, 3, 0)>(vb), h3 = tr_read<v_rd_off(D0, 3, 1)>(vb);
;   asm volatile("s_waitcnt lgkmcnt(0)" ::: "memory"); SBAR();
;     ...
;   od = __builtin_amdgcn_mfma_f32_32x32x16_bf16(pa0, PK(l0, h0), od, 0, 0, 0);
;   od = __builtin_amdgcn_mfma_f32_32x32x16_bf16(pa1, PK(l1, h1), od, 0, 0, 0);
;   od = __builtin_amdgcn_mfma_f32_32x32x16_bf16(pa2, PK(l2, h2), od, 0, 0, 0);
;   od = __builtin_amdgcn_mfma_f32_32x32x16_bf16(pa3, PK(l3, h3), od, 0, 0, 0);
;     ...
; }
; __device__ __forceinline__ void pv_d0(f32x16 (&o)[4], int vb, bf16x8 pa0, bf16x8 pa1, bf16x8 pa2, bf16x8 pa3) {
;   pv_one<0>(o[0], vb, pa0, pa1, pa2, pa3); pv_one<1>(o[1], vb, pa0, pa1, pa2, pa3); pv_one<2>(o[2], vb, pa0, pa1, pa2, pa3); pv_one<3>(o[3], vb, pa0, pa1, pa2, pa3);
; }
	v_mfma_f32_32x32x16_bf16 v[98:113], v[200:203], v[148:151], v[98:113]
	ds_read_b64_tr_b16 v[236:237], v191 offset:8192
	ds_read_b64_tr_b16 v[238:239], v191 offset:10240
	s_mov_b64 s[22:23], 0x61e0c180
	s_add_i32 m0, s11, 0x400
	v_lshl_add_u64 v[192:193], v[164:165], 0, s[22:23]
	global_load_lds_dwordx4 v[192:193], off
	v_cvt_pk_bf16_f32 v71, v76, v77
	v_add_f32_e32 v196, v78, v196
	v_add_f32_e32 v197, v79, v197
	v_cvt_pk_bf16_f32 v72, v78, v79
	s_waitcnt lgkmcnt(8)
	v_mfma_f32_32x32x16_bf16 v[212:227], v[204:207], v[148:151], v[212:227]
	ds_read_b128 v[200:203], v190 offset:256
	ds_read_b128 v[204:207], v190 offset:12544
	ds_read_b64_tr_b16 v[240:241], v191 offset:12288
	ds_read_b64_tr_b16 v[242:243], v191 offset:14336
	v_add_f32_e32 v196, v80, v196
	v_add_f32_e32 v197, v81, v197
	v_cvt_pk_bf16_f32 v73, v80, v81
	s_waitcnt lgkmcnt(9)
	v_mfma_f32_32x32x16_bf16 v[98:113], v[172:175], v[160:163], v[98:113]
	ds_read_b64_tr_b16 v[246:247], v191 offset:512
	ds_read_b64_tr_b16 v[248:249], v191 offset:2560
	v_add_f32_e32 v196, v196, v197
	s_nop 0
	v_permlane32_swap_b32_e32 v66, v68
	v_permlane32_swap_b32_e32 v67, v69
	s_waitcnt lgkmcnt(10)
	v_mfma_f32_32x32x16_bf16 v[212:227], v[176:179], v[160:163], v[212:227]
	ds_read_b64_tr_b16 v[250:251], v191 offset:4608
	ds_read_b64_tr_b16 v[252:253], v191 offset:6656
	v_permlane32_swap_b32_e32 v70, v72
	v_permlane32_swap_b32_e32 v71, v73
	v_add_f32_e32 v114, v114, v196
	s_waitcnt lgkmcnt(7)
	v_mfma_f32_32x32x16_bf16 v[98:113], v[200:203], v[156:159], v[98:113]
	s_waitcnt lgkmcnt(6)
	v_mfma_f32_32x32x16_bf16 v[212:227], v[204:207], v[156:159], v[212:227]
	v_mfma_f32_32x32x16_bf16 v[2:17], v[82:85], v[228:231], v[2:17]
	ds_read_b64_tr_b16 v[228:229], v191 offset:8704
	ds_read_b64_tr_b16 v[230:231], v191 offset:10752
	v_mfma_f32_32x32x16_bf16 v[2:17], v[86:89], v[232:235], v[2:17]
	ds_read_b64_tr_b16 v[232:233], v191 offset:12800
	ds_read_b64_tr_b16 v[234:235], v191 offset:14848
	v_mfma_f32_32x32x16_bf16 v[2:17], v[66:69], v[236:239], v[2:17]
	ds_read_b64_tr_b16 v[236:237], v191 offset:1024
	ds_read_b64_tr_b16 v[238:239], v191 offset:3072
	s_waitcnt lgkmcnt(10)
	v_mfma_f32_32x32x16_bf16 v[2:17], v[70:73], v[240:243], v[2:17]
	ds_read_b64_tr_b16 v[240:241], v191 offset:5120
	ds_read_b64_tr_b16 v[242:243], v191 offset:7168
	v_exp_f32_e32 v98, v98
	s_waitcnt lgkmcnt(10)
	v_mfma_f32_32x32x16_bf16 v[18:33], v[82:85], v[246:249], v[18:33]
	ds_read_b64_tr_b16 v[246:247], v191 offset:9216
	ds_read_b64_tr_b16 v[248:249], v191 offset:11264
	v_exp_f32_e32 v99, v99
	s_waitcnt lgkmcnt(10)
	v_mfma_f32_32x32x16_bf16 v[18:33], v[86:89], v[250:253], v[18:33]
	ds_read_b64_tr_b16 v[250:251], v191 offset:13312
	ds_read_b64_tr_b16 v[252:253], v191 offset:15360
	v_exp_f32_e32 v100, v100
	s_waitcnt lgkmcnt(10)
	v_mfma_f32_32x32x16_bf16 v[18:33], v[66:69], v[228:231], v[18:33]
	ds_read_b64_tr_b16 v[228:229], v191 offset:1536
	ds_read_b64_tr_b16 v[230:231], v191 offset:3584
	v_exp_f32_e32 v101, v101
	s_waitcnt lgkmcnt(10)
	v_mfma_f32_32x32x16_bf16 v[18:33], v[70:73], v[232:235], v[18:33]
	ds_read_b64_tr_b16 v[232:233], v191 offset:5632
	ds_read_b64_tr_b16 v[234:235], v191 offset:7680
	v_exp_f32_e32 v102, v102
	s_waitcnt lgkmcnt(10)
	v_mfma_f32_32x32x16_bf16 v[34:49], v[82:85], v[236:239], v[34:49]
	ds_read_b64_tr_b16 v[236:237], v191 offset:9728
	ds_read_b64_tr_b16 v[238:239], v191 offset:11776
	v_exp_f32_e32 v103, v103
	s_waitcnt lgkmcnt(10)
	v_mfma_f32_32x32x16_bf16 v[34:49], v[86:89], v[240:243], v[34:49]
	ds_read_b64_tr_b16 v[240:241], v191 offset:13824
	ds_read_b64_tr_b16 v[242:243], v191 offset:15872
	v_exp_f32_e32 v104, v104
	s_waitcnt lgkmcnt(10)
	v_mfma_f32_32x32x16_bf16 v[34:49], v[66:69], v[246:249], v[34:49]
	v_exp_f32_e32 v105, v105
	s_waitcnt lgkmcnt(8)
	v_mfma_f32_32x32x16_bf16 v[34:49], v[70:73], v[250:253], v[34:49]
	v_exp_f32_e32 v106, v106
	s_waitcnt lgkmcnt(6)
	v_mfma_f32_32x32x16_bf16 v[50:65], v[82:85], v[228:231], v[50:65]
	v_exp_f32_e32 v107, v107
	v_exp_f32_e32 v108, v108
	s_waitcnt lgkmcnt(4)
	v_mfma_f32_32x32x16_bf16 v[50:65], v[86:89], v[232:235], v[50:65]
	v_exp_f32_e32 v109, v109
	v_exp_f32_e32 v110, v110
	s_waitcnt lgkmcnt(2)
	v_mfma_f32_32x32x16_bf16 v[50:65], v[66:69], v[236:239], v[50:65]
	v_exp_f32_e32 v111, v111
	v_exp_f32_e32 v112, v112
	s_waitcnt lgkmcnt(0)
	v_mfma_f32_32x32x16_bf16 v[50:65], v[70:73], v[240:243], v[50:65]
	v_exp_f32_e32 v113, v113
	s_waitcnt vmcnt(5)
	s_barrier
; __device__ __forceinline__ void finishSM_fix(f32x16& p0, f32x16& p1, float& l_lane, bf16x8& pa0, bf16x8& pa1, bf16x8& pa2, bf16x8& pa3) {
; #pragma unroll
;   for (int r = 0; r < 16; ++r) p1[r] = __builtin_amdgcn_exp2f(p1[r]);
;   float ps = 0;
; #pragma unroll
;   for (int r = 0; r < 16; ++r) ps += p0[r];
; #pragma unroll
;   for (int r = 0; r < 16; ++r) ps += p1[r];
;   l_lane += ps;
;     ...
;   PK4(p0, 0, pa0); PK4(p0, 8, pa1); PK4(p1, 0, pa2); PK4(p1, 8, pa3);
; __device__ __forceinline__ void qkt12(f32x16& p0, f32x16& p1, const char* Ks, const bf16x8 (&qr)[12], const int (&kb)[4]) {
;   p0 = f32x16{}; p1 = f32x16{};
;     ...
;   bf16x8 c0 = KLD(0, 0), c1 = KLD(0, 1);
; #pragma unroll
;   for (int d0 = 0; d0 < 12; ++d0) {
;     bf16x8 n0 = c0, n1 = c1;
;     if (d0 < 11) { n0 = KLD(d0 + 1, 0); n1 = KLD(d0 + 1, 1); }
;     __builtin_amdgcn_sched_group_barrier(0x100, 2, 0);
;     p0 = __builtin_amdgcn_mfma_f32_32x32x16_bf16(c0, qr[d0], p0, 0, 0, 0);
;     p1 = __builtin_amdgcn_mfma_f32_32x32x16_bf16(c1, qr[d0], p1, 0, 0, 0);
;     __builtin_amdgcn_sched_group_barrier(0x008, 2, 0);
;     c0 = n0; c1 = n1; }
;     ...
; }
	s_mul_i32 s6, s25, 0x6000
	s_mul_i32 s10, s24, 0x6000
	s_lshl_b32 s11, s26, 14
	s_add_i32 s10, s43, s10
	s_add_i32 s11, s52, s11
	v_add_u32_e32 v187, s6, v183
	v_add_u32_e32 v188, s6, v184
	v_add_u32_e32 v189, s6, v185
	v_add_u32_e32 v190, s6, v186
	v_lshl_add_u32 v191, s24, 14, v182
	ds_read_b128 v[172:175], v187
	ds_read_b128 v[176:179], v187 offset:12288
	ds_read_b128 v[200:203], v188
	ds_read_b128 v[204:207], v188 offset:12288
	v_add_f32_e32 v196, v98, v99
	v_cvt_pk_bf16_f32 v98, v98, v99
	v_add_f32_e32 v197, v100, v101
	v_exp_f32_e32 v212, v212
	v_exp_f32_e32 v213, v213
	v_cvt_pk_bf16_f32 v99, v100, v101
	v_add_f32_e32 v196, v102, v196
	v_add_f32_e32 v197, v103, v197
	s_waitcnt lgkmcnt(3)
	v_mfma_f32_32x32x16_bf16 v[82:97], v[172:175], v[116:119], 0
	v_exp_f32_e32 v214, v214
	v_exp_f32_e32 v215, v215
	s_waitcnt lgkmcnt(2)
	v_mfma_f32_32x32x16_bf16 v[66:81], v[176:179], v[116:119], 0
	ds_read_b128 v[172:175], v189
	ds_read_b128 v[176:179], v189 offset:12288
	v_cvt_pk_bf16_f32 v100, v102, v103
	v_add_f32_e32 v196, v104, v196
	v_add_f32_e32 v197, v105, v197
	v_exp_f32_e32 v216, v216
	s_waitcnt lgkmcnt(3)
	v_mfma_f32_32x32x16_bf16 v[82:97], v[200:203], v[120:123], v[82:97]
	s_mov_b32 m0, s10
	v_lshl_add_u64 v[192:193], v[166:167], 0, s[94:95]
	global_load_lds_dwordx4 v[192:193], off
	v_exp_f32_e32 v217, v217
	s_waitcnt lgkmcnt(2)
	v_mfma_f32_32x32x16_bf16 v[66:81], v[204:207], v[120:123], v[66:81]
	ds_read_b128 v[200:203], v190
	ds_read_b128 v[204:207], v190 offset:12288
	v_cvt_pk_bf16_f32 v101, v104, v105
	v_add_f32_e32 v196, v106, v196
	v_add_f32_e32 v197, v107, v197
	v_exp_f32_e32 v218, v218
	s_waitcnt lgkmcnt(3)
	v_mfma_f32_32x32x16_bf16 v[82:97], v[172:175], v[124:127], v[82:97]
	v_exp_f32_e32 v219, v219
	s_waitcnt lgkmcnt(2)
	v_mfma_f32_32x32x16_bf16 v[66:81], v[176:179], v[124:127], v[66:81]
	ds_read_b128 v[172:175], v187 offset:128
	ds_read_b128 v[176:179], v187 offset:12416
	v_cvt_pk_bf16_f32 v102, v106, v107
	v_add_f32_e32 v196, v108, v196
	v_add_f32_e32 v197, v109, v197
	v_exp_f32_e32 v220, v220
	s_waitcnt lgkmcnt(3)
	v_mfma_f32_32x32x16_bf16 v[82:97], v[200:203], v[128:131], v[82:97]
	s_add_i32 m0, s10, 0x400
	v_lshl_add_u64 v[192:193], v[168:169], 0, s[94:95]
	global_load_lds_dwordx4 v[192:193], off
	v_exp_f32_e32 v221, v221
	v_cvt_pk_bf16_f32 v103, v108, v109
	s_waitcnt lgkmcnt(2)
	v_mfma_f32_32x32x16_bf16 v[66:81], v[204:207], v[128:131], v[66:81]
	ds_read_b128 v[200:203], v188 offset:128
	ds_read_b128 v[204:207], v188 offset:12416
	v_add_f32_e32 v196, v110, v196
	v_add_f32_e32 v197, v111, v197
	v_exp_f32_e32 v222, v222
	s_waitcnt lgkmcnt(3)
	v_mfma_f32_32x32x16_bf16 v[82:97], v[172:175], v[132:135], v[82:97]
	v_exp_f32_e32 v223, v223
	v_cvt_pk_bf16_f32 v104, v110, v111
	s_waitcnt lgkmcnt(2)
	v_mfma_f32_32x32x16_bf16 v[66:81], v[176:179], v[132:135], v[66:81]
	ds_read_b128 v[172:175], v189 offset:128
	ds_read_b128 v[176:179], v189 offset:12416
	v_add_f32_e32 v196, v112, v196
	v_add_f32_e32 v197, v113, v197
	v_exp_f32_e32 v224, v224
	s_waitcnt lgkmcnt(3)
	v_mfma_f32_32x32x16_bf16 v[82:97], v[200:203], v[136:139], v[82:97]
	s_add_i32 m0, s10, 0x800
	v_lshl_add_u64 v[192:193], v[170:171], 0, s[94:95]
	global_load_lds_dwordx4 v[192:193], off
	v_exp_f32_e32 v225, v225
	v_cvt_pk_bf16_f32 v105, v112, v113
	s_waitcnt lgkmcnt(2)
	v_mfma_f32_32x32x16_bf16 v[66:81], v[204:207], v[136:139], v[66:81]
	ds_read_b128 v[200:203], v190 offset:128
	ds_read_b128 v[204:207], v190 offset:12416
	v_exp_f32_e32 v226, v226
	v_exp_f32_e32 v227, v227
	s_waitcnt lgkmcnt(3)
	v_mfma_f32_32x32x16_bf16 v[82:97], v[172:175], v[140:143], v[82:97]
	v_add_f32_e32 v196, v212, v196
	v_add_f32_e32 v197, v213, v197
	v_cvt_pk_bf16_f32 v212, v212, v213
	s_waitcnt lgkmcnt(2)
	v_mfma_f32_32x32x16_bf16 v[66:81], v[176:179], v[140:143], v[66:81]
	ds_read_b128 v[172:175], v187 offset:256
	ds_read_b128 v[176:179], v187 offset:12544
	v_permlane32_swap_b32_e32 v98, v100
	v_permlane32_swap_b32_e32 v99, v101
	v_permlane32_swap_b32_e32 v102, v104
	v_permlane32_swap_b32_e32 v103, v105
	s_waitcnt lgkmcnt(3)
	v_mfma_f32_32x32x16_bf16 v[82:97], v[200:203], v[144:147], v[82:97]
	s_mov_b64 s[22:23], 0x61e8c100
	s_mov_b32 m0, s11
	v_lshl_add_u64 v[192:193], v[164:165], 0, s[22:23]
	global_load_lds_dwordx4 v[192:193], off
	v_add_f32_e32 v196, v214, v196
	v_add_f32_e32 v197, v215, v197
	v_cvt_pk_bf16_f32 v213, v214, v215
	s_waitcnt lgkmcnt(2)
	v_mfma_f32_32x32x16_bf16 v[66:81], v[204:207], v[144:147], v[66:81]
	ds_read_b128 v[200:203], v188 offset:256
	ds_read_b128 v[204:207], v188 offset:12544
	v_add_f32_e32 v196, v216, v196
	v_add_f32_e32 v197, v217, v197
	v_cvt_pk_bf16_f32 v214, v216, v217
	v_add_f32_e32 v196, v218, v196
	s_waitcnt lgkmcnt(3)
	v_mfma_f32_32x32x16_bf16 v[82:97], v[172:175], v[152:155], v[82:97]
	ds_read_b64_tr_b16 v[228:229], v191 offset:0
	ds_read_b64_tr_b16 v[230:231], v191 offset:2048
	v_add_f32_e32 v197, v219, v197
	v_cvt_pk_bf16_f32 v215, v218, v219
	v_add_f32_e32 v196, v220, v196
	v_add_f32_e32 v197, v221, v197
	s_waitcnt lgkmcnt(4)
	v_mfma_f32_32x32x16_bf16 v[66:81], v[176:179], v[152:155], v[66:81]
	ds_read_b128 v[172:175], v189 offset:256
	ds_read_b128 v[176:179], v189 offset:12544
	ds_read_b64_tr_b16 v[232:233], v191 offset:4096
	ds_read_b64_tr_b16 v[234:235], v191 offset:6144
	v_cvt_pk_bf16_f32 v216, v220, v221
	v_add_f32_e32 v196, v222, v196
	v_add_f32_e32 v197, v223, v197
	s_waitcnt lgkmcnt(7)
; #define SBAR() __builtin_amdgcn_sched_barrier(0)
; #define TOP(t, st) do { if ((t) + 2 < NT) asm volatile("s_waitcnt vmcnt(5)" ::: "memory"); else asm volatile("s_waitcnt vmcnt(0)" ::: "memory"); \
;     __builtin_amdgcn_s_barrier(); asm volatile("" ::: "memory"); \
;     if ((t) + 2 < NT) KDMA((t) + 2, NEXT3(NEXT3(st))); if ((t) + 1 < NT) VDMA((t) + 1, NEXT3(st)); } while (0)
; template <int OFF> __device__ __forceinline__ s16x4 tr_read(int vb) {
;   s16x4 r; asm volatile("ds_read_b64_tr_b16 %0, %1 offset:%2" : "=&v"(r) : "v"(vb), "i"(OFF) : "memory"); return r;
; }
; template <int D0> __device__ __forceinline__ void pv_one(f32x16& od, int vb, bf16x8 pa0, bf16x8 pa1, bf16x8 pa2, bf16x8 pa3) {
;   const s16x4 l0 = tr_read<v_rd_off(D0, 0, 0)>(vb), h0 = tr_read<v_rd_off(D0, 0, 1)>(vb), l1 = tr_read<v_rd_off(D0, 1, 0)>(vb), h1 = tr_read<v_rd_off(D0, 1, 1)>(vb);
;   const s16x4 l2 = tr_read<v_rd_off(D0, 2, 0)>(vb), h2 = tr_read<v_rd_off(D0, 2, 1)>(vb), l3 = tr_read<v_rd_off(D0, 3, 0)>(vb), h3 = tr_read<v_rd_off(D0, 3, 1)>(vb);
;   asm volatile("s_waitcnt lgkmcnt(0)" ::: "memory"); SBAR();
;     ...
;   od = __builtin_amdgcn_mfma_f32_32x32x16_bf16(pa0, PK(l0, h0), od, 0, 0, 0);
;   od = __builtin_amdgcn_mfma_f32_32x32x16_bf16(pa1, PK(l1, h1), od, 0, 0, 0);
;   od = __builtin_amdgcn_mfma_f32_32x32x16_bf16(pa2, PK(l2, h2), od, 0, 0, 0);
;   od = __builtin_amdgcn_mfma_f32_32x32x16_bf16(pa3, PK(l3, h3), od, 0, 0, 0);
;     ...
; }
; __device__ __forceinline__ void pv_d0(f32x16 (&o)[4], int vb, bf16x8 pa0, bf16x8 pa1, bf16x8 pa2, bf16x8 pa3) {
;   pv_one<0>(o[0], vb, pa0, pa1, pa2, pa3); pv_one<1>(o[1], vb, pa0, pa1, pa2, pa3); pv_one<2>(o[2], vb, pa0, pa1, pa2, pa3); pv_one<3>(o[3], vb, pa0, pa1, pa2, pa3);
; }
; __device__ __forceinline__ void attn_unit_dma(const bf16_t* __restrict__ Qb, const bf16_t* __restrict__ Kh, const bf16_t* __restrict__ Vh, int seq, char* lds, LAS unsigned char* ldsl, ...
;     ...
;     sp = st; st = NEXT3(st);
;     TOP(j + 1, st);
;     SBAR(); qkt12(pA0, pA1, lds + DMA_KRING + st * SHM_K, qr, kb);
;     finishSM_fix(pB0, pB1, l_reg, pa0, pa1, pa2, pa3); SBAR();
;     pv_d0(o, vb0 + sp * SHM_V, pa0, pa1, pa2, pa3); partialSM_fix(pA0, pA1);
;   }
	v_mfma_f32_32x32x16_bf16 v[82:97], v[200:203], v[148:151], v[82:97]
	ds_read_b64_tr_b16 v[236:237], v191 offset:8192
	ds_read_b64_tr_b16 v[238:239], v191 offset:10240
	s_mov_b64 s[22:23], 0x61e8c180
	s_add_i32 m0, s11, 0x400
	v_lshl_add_u64 v[192:193], v[164:165], 0, s[22:23]
	global_load_lds_dwordx4 v[192:193], off
	v_cvt_pk_bf16_f32 v217, v222, v223
	v_add_f32_e32 v196, v224, v196
	v_add_f32_e32 v197, v225, v197
	v_cvt_pk_bf16_f32 v218, v224, v225
	s_waitcnt lgkmcnt(8)
	v_mfma_f32_32x32x16_bf16 v[66:81], v[204:207], v[148:151], v[66:81]
	ds_read_b128 v[200:203], v190 offset:256
	ds_read_b128 v[204:207], v190 offset:12544
	ds_read_b64_tr_b16 v[240:241], v191 offset:12288
	ds_read_b64_tr_b16 v[242:243], v191 offset:14336
	v_add_f32_e32 v196, v226, v196
	v_add_f32_e32 v197, v227, v197
	v_cvt_pk_bf16_f32 v219, v226, v227
	s_waitcnt lgkmcnt(9)
	v_mfma_f32_32x32x16_bf16 v[82:97], v[172:175], v[160:163], v[82:97]
	ds_read_b64_tr_b16 v[246:247], v191 offset:512
	ds_read_b64_tr_b16 v[248:249], v191 offset:2560
	v_add_f32_e32 v196, v196, v197
	s_nop 0
	v_permlane32_swap_b32_e32 v212, v214
	v_permlane32_swap_b32_e32 v213, v215
	s_waitcnt lgkmcnt(10)
	v_mfma_f32_32x32x16_bf16 v[66:81], v[176:179], v[160:163], v[66:81]
	ds_read_b64_tr_b16 v[250:251], v191 offset:4608
	ds_read_b64_tr_b16 v[252:253], v191 offset:6656
	v_permlane32_swap_b32_e32 v216, v218
	v_permlane32_swap_b32_e32 v217, v219
	v_add_f32_e32 v114, v114, v196
	s_waitcnt lgkmcnt(7)
	v_mfma_f32_32x32x16_bf16 v[82:97], v[200:203], v[156:159], v[82:97]
	s_waitcnt lgkmcnt(6)
	v_mfma_f32_32x32x16_bf16 v[66:81], v[204:207], v[156:159], v[66:81]
	v_mfma_f32_32x32x16_bf16 v[2:17], v[98:101], v[228:231], v[2:17]
	ds_read_b64_tr_b16 v[228:229], v191 offset:8704
	ds_read_b64_tr_b16 v[230:231], v191 offset:10752
	v_mfma_f32_32x32x16_bf16 v[2:17], v[102:105], v[232:235], v[2:17]
	ds_read_b64_tr_b16 v[232:233], v191 offset:12800
	ds_read_b64_tr_b16 v[234:235], v191 offset:14848
	v_mfma_f32_32x32x16_bf16 v[2:17], v[212:215], v[236:239], v[2:17]
	ds_read_b64_tr_b16 v[236:237], v191 offset:1024
	ds_read_b64_tr_b16 v[238:239], v191 offset:3072
	v_lshl_add_u64 v[166:167], v[166:167], 0, s[90:91]
	s_waitcnt lgkmcnt(10)
	v_mfma_f32_32x32x16_bf16 v[2:17], v[216:219], v[240:243], v[2:17]
	ds_read_b64_tr_b16 v[240:241], v191 offset:5120
	ds_read_b64_tr_b16 v[242:243], v191 offset:7168
	v_exp_f32_e32 v82, v82
	v_lshl_add_u64 v[168:169], v[168:169], 0, s[90:91]
	s_waitcnt lgkmcnt(10)
	v_mfma_f32_32x32x16_bf16 v[18:33], v[98:101], v[246:249], v[18:33]
	ds_read_b64_tr_b16 v[246:247], v191 offset:9216
	ds_read_b64_tr_b16 v[248:249], v191 offset:11264
	v_exp_f32_e32 v83, v83
	v_lshl_add_u64 v[170:171], v[170:171], 0, s[90:91]
	s_waitcnt lgkmcnt(10)
	v_mfma_f32_32x32x16_bf16 v[18:33], v[102:105], v[250:253], v[18:33]
	ds_read_b64_tr_b16 v[250:251], v191 offset:13312
	ds_read_b64_tr_b16 v[252:253], v191 offset:15360
	v_exp_f32_e32 v84, v84
	v_lshl_add_u64 v[164:165], v[164:165], 0, s[68:69]
	s_waitcnt lgkmcnt(10)
	v_mfma_f32_32x32x16_bf16 v[18:33], v[212:215], v[228:231], v[18:33]
	ds_read_b64_tr_b16 v[228:229], v191 offset:1536
	ds_read_b64_tr_b16 v[230:231], v191 offset:3584
	v_exp_f32_e32 v85, v85
	s_waitcnt lgkmcnt(10)
	v_mfma_f32_32x32x16_bf16 v[18:33], v[216:219], v[232:235], v[18:33]
	ds_read_b64_tr_b16 v[232:233], v191 offset:5632
	ds_read_b64_tr_b16 v[234:235], v191 offset:7680
	v_exp_f32_e32 v86, v86
	s_waitcnt lgkmcnt(10)
	v_mfma_f32_32x32x16_bf16 v[34:49], v[98:101], v[236:239], v[34:49]
	ds_read_b64_tr_b16 v[236:237], v191 offset:9728
	ds_read_b64_tr_b16 v[238:239], v191 offset:11776
	v_exp_f32_e32 v87, v87
	s_waitcnt lgkmcnt(10)
	v_mfma_f32_32x32x16_bf16 v[34:49], v[102:105], v[240:243], v[34:49]
	ds_read_b64_tr_b16 v[240:241], v191 offset:13824
	ds_read_b64_tr_b16 v[242:243], v191 offset:15872
	v_exp_f32_e32 v88, v88
	s_waitcnt lgkmcnt(10)
	v_mfma_f32_32x32x16_bf16 v[34:49], v[212:215], v[246:249], v[34:49]
	v_exp_f32_e32 v89, v89
	s_waitcnt lgkmcnt(8)
	v_mfma_f32_32x32x16_bf16 v[34:49], v[216:219], v[250:253], v[34:49]
	v_exp_f32_e32 v90, v90
	s_waitcnt lgkmcnt(6)
	v_mfma_f32_32x32x16_bf16 v[50:65], v[98:101], v[228:231], v[50:65]
	v_exp_f32_e32 v91, v91
	v_exp_f32_e32 v92, v92
	s_waitcnt lgkmcnt(4)
	v_mfma_f32_32x32x16_bf16 v[50:65], v[102:105], v[232:235], v[50:65]
	v_exp_f32_e32 v93, v93
	v_exp_f32_e32 v94, v94
	s_waitcnt lgkmcnt(2)
	v_mfma_f32_32x32x16_bf16 v[50:65], v[212:215], v[236:239], v[50:65]
	v_exp_f32_e32 v95, v95
	v_exp_f32_e32 v96, v96
	s_waitcnt lgkmcnt(0)
	v_mfma_f32_32x32x16_bf16 v[50:65], v[216:219], v[240:243], v[50:65]
	v_exp_f32_e32 v97, v97
	s_mov_b32 s26, s25
	s_add_i32 s72, s72, 2
	s_cmp_lt_u32 s72, s37
	s_cbranch_scc1 .Lfa_loop
	v_mov_b32_e32 v195, v82
	v_mov_b32_e32 v216, v83
	v_mov_b32_e32 v213, v84
	v_mov_b32_e32 v215, v85
	v_mov_b32_e32 v197, v86
	v_mov_b32_e32 v214, v87
	v_mov_b32_e32 v196, v88
	v_mov_b32_e32 v212, v89
	v_mov_b32_e32 v191, v90
	v_mov_b32_e32 v193, v91
	v_mov_b32_e32 v189, v92
	v_mov_b32_e32 v192, v93
	v_mov_b32_e32 v188, v94
	v_mov_b32_e32 v190, v95
	v_mov_b32_e32 v187, v96
	v_mov_b32_e32 v194, v97
	s_branch .LBB0_853
